# FFN2 conversion split: 1120 tiles in the out-projection GEMM idle workgroups, 992 in the scan-phase tail
# baseline (speedup 1.0000x reference)
; __device__ __forceinline__ int fresh_tid(int wv) { int l; asm volatile("v_mbcnt_lo_u32_b32 %0, -1, 0\n\tv_mbcnt_hi_u32_b32 %0, -1, %0" : "=v"(l)); return wv * 64 + l; }
; #define LAS __attribute__((address_space(3)))
; __device__ __forceinline__ TDesc tconv_desc(const float* wg, const float* wu, const float* wd, const float* win, const float* wout, unsigned char* ws, int i) {
;     TDesc d; int mode = 0, tile = i;
;     if (i < 704) { d.W = wg; d.Bt = (bf16_t*)(ws + WS_WGU); d.K = 1024; d.N = DFF; mode = 1; }
;     else if (i < 1408) { d.W = wu; d.Bt = (bf16_t*)(ws + WS_WGU); d.K = 1024; d.N = DFF; mode = 2; tile = i - 704; }
;     else if (i < 2112) { d.W = wd; d.Bt = (bf16_t*)(ws + WS_WD); d.K = DFF; d.N = 1024; tile = i - 1408; }
;     else if (i < 3072) { d.W = win; d.Bt = (bf16_t*)(ws + WS_WIN); d.K = 1024; d.N = NCOLS; tile = i - 2112; }
;     else { d.W = wout; d.Bt = (bf16_t*)(ws + WS_WOUT); d.K = 1024; d.N = 1024; tile = i - 3072; }
;     const int nkt = d.K / 64; const int kt = tile % nkt, nt = tile / nkt; d.k0 = kt * 64; d.n0 = nt * 64;
;     d.brow0 = mode == 0 ? d.n0 : ((d.n0 >> 7) * 256 + (d.n0 & 127) + (mode == 2 ? 128 : 0));
;     return d;
; }
; __device__ __forceinline__ void tconv_list(const float* wg, const float* wu, const float* wd, const float* win, const float* wout, unsigned char* ws, const int ntiles, LAS float* t, const int wv) {
;     const int tid = fresh_tid(wv); const int G = gridDim.x;
;     float cur[8], nxt[8];
;     int i = blockIdx.x;
;     if (i < ntiles) { const TDesc d = tconv_desc(wg, wu, wd, win, wout, ws, i);
; #pragma unroll
;         for (int e = 0; e < 8; ++e) { const int idx = e * 512 + tid, r = idx >> 6, c = idx & 63; cur[e] = __builtin_nontemporal_load(d.W + (size_t)(d.k0 + r) * d.N + d.n0 + c); } }
.LBB0_689:
	s_cmp_lt_u32 s2, 128
	s_cbranch_scc1 .Ltc2_skip
	v_writelane_b32 v40, s4, 4
	v_writelane_b32 v40, s5, 5
	v_writelane_b32 v40, s6, 6
	v_writelane_b32 v40, s7, 7
	v_writelane_b32 v40, s8, 8
	v_writelane_b32 v40, s9, 9
	v_writelane_b32 v40, s10, 10
	v_writelane_b32 v40, s11, 11
	v_writelane_b32 v40, s12, 12
	v_writelane_b32 v40, s13, 13
	v_writelane_b32 v40, s14, 14
	v_writelane_b32 v40, s15, 15
	v_writelane_b32 v40, s16, 16
	v_writelane_b32 v40, s17, 17
	v_writelane_b32 v40, s18, 18
	v_writelane_b32 v40, s19, 19
	v_writelane_b32 v40, s20, 20
	v_writelane_b32 v40, s21, 21
	v_writelane_b32 v40, s22, 22
	v_writelane_b32 v40, s23, 23
	v_writelane_b32 v40, s24, 24
	v_writelane_b32 v40, s25, 25
	v_writelane_b32 v40, s26, 26
	v_writelane_b32 v40, s27, 27
	v_writelane_b32 v40, s28, 28
	v_writelane_b32 v40, s29, 29
	v_writelane_b32 v40, s30, 30
	v_writelane_b32 v40, s31, 31
	s_load_dwordx2 s[24:25], s[38:39], 0xd8
	s_load_dwordx2 s[26:27], s[38:39], 0xd0
	s_load_dwordx2 s[18:19], s[38:39], 0xb8
	s_load_dwordx2 s[20:21], s[38:39], 0xc0
	s_load_dwordx2 s[22:23], s[38:39], 0xc8
	v_mbcnt_lo_u32_b32 v0, -1, 0
	v_mbcnt_hi_u32_b32 v0, -1, v0
	s_lshr_b32 s28, s33, 6
	v_lshlrev_b32_e32 v1, 2, v0
	v_lshrrev_b32_e32 v2, 5, v0
	v_and_b32_e32 v3, 31, v0
	s_mul_i32 s7, s28, 260
	v_add_u32_e32 v5, s7, v1
	v_mul_u32_u24_e32 v6, 0x208, v3
	s_lshl_b32 s7, s28, 3
	v_lshl_add_u32 v6, v2, 2, v6
	v_add_u32_e32 v6, s7, v6
	v_lshlrev_b32_e32 v3, 2, v3
	s_sub_u32 s4, s2, 128
	s_add_u32 s4, s4, 1120
	s_waitcnt lgkmcnt(0)
	s_cmp_lt_u32 s4, 704
	s_cbranch_scc0 .Ltc2_seg1_0
	s_mov_b32 s7, s4
	s_and_b32 s8, s7, 15
	s_lshr_b32 s9, s7, 4
	s_mul_i32 s7, s8, 720896
	s_lshl_b32 s29, s9, 8
	s_add_u32 s7, s7, s29
	s_mul_i32 s29, s28, 11264
	s_add_u32 s7, s7, s29
	s_add_u32 s10, s18, s7
	s_addc_u32 s11, s19, 0
	s_lshr_b32 s7, s9, 1
	s_lshl_b32 s7, s7, 8
	s_and_b32 s29, s9, 1
	s_lshl_b32 s29, s29, 6
	s_add_u32 s7, s7, s29
	s_mul_i32 s7, s7, 2048
	s_lshl_b32 s29, s8, 7
	s_add_u32 s7, s7, s29
	s_mul_i32 s29, s28, 4096
	s_add_u32 s7, s7, s29
	s_add_u32 s12, s26, 0x2100000
	s_addc_u32 s13, s27, 0
	s_add_u32 s12, s12, s7
	s_addc_u32 s13, s13, 0
	s_mov_b32 s14, 90112
	s_mov_b32 s15, 32768
	s_movk_i32 s16, 2048
	s_branch .Ltc2_segend_0

; __device__ __forceinline__ void tconv_list(const float* wg, const float* wu, const float* wd, const float* win, const float* wout, unsigned char* ws, const int ntiles, LAS float* t, const int wv) {
;     ...
;     for (; i < ntiles; i += G) {
;         const TDesc d = tconv_desc(wg, wu, wd, win, wout, ws, i);
;         { const TDesc dn = tconv_desc(wg, wu, wd, win, wout, ws, i + G < ntiles ? i + G : i);
; #pragma unroll
;             for (int e = 0; e < 8; ++e) { const int idx = e * 512 + tid, r = idx >> 6, c = idx & 63; nxt[e] = __builtin_nontemporal_load(dn.W + (size_t)(dn.k0 + r) * dn.N + dn.n0 + c); } }
.Ltc4_loop:
	s_add_u32 s4, s4, 224
	s_cmp_lt_u32 s4, 1120
	s_cselect_b32 s31, 1, 0
	s_cbranch_scc0 .Ltc4_nonexta
	v_writelane_b32 v40, s8, 32
	v_writelane_b32 v40, s9, 33
	s_cmp_lt_u32 s4, 704
	s_cbranch_scc0 .Ltc4_seg1_1
	s_mov_b32 s7, s4
	s_and_b32 s8, s7, 15
	s_lshr_b32 s9, s7, 4
	s_mul_i32 s7, s8, 720896
	s_lshl_b32 s29, s9, 8
	s_add_u32 s7, s7, s29
	s_mul_i32 s29, s28, 11264
	s_add_u32 s7, s7, s29
	s_add_u32 s10, s18, s7
	s_addc_u32 s11, s19, 0
	s_lshr_b32 s7, s9, 1
	s_lshl_b32 s7, s7, 8
	s_and_b32 s29, s9, 1
	s_lshl_b32 s29, s29, 6
	s_add_u32 s7, s7, s29
	s_mul_i32 s7, s7, 2048
	s_lshl_b32 s29, s8, 7
	s_add_u32 s7, s7, s29
	s_mul_i32 s29, s28, 4096
	s_add_u32 s7, s7, s29
	s_add_u32 s12, s26, 0x2100000
	s_addc_u32 s13, s27, 0
	s_add_u32 s12, s12, s7
	s_addc_u32 s13, s13, 0
	s_mov_b32 s14, 90112
	s_mov_b32 s15, 32768
	s_movk_i32 s16, 2048
	s_branch .Ltc4_segend_1

; __device__ __forceinline__ unsigned cvt_pk_bf16(float lo, float hi) { const f32x2_t v = {lo, hi}; const bf16x2_t b = __builtin_convertvector(v, bf16x2_t); return __builtin_bit_cast(unsigned, b); }
; __device__ __forceinline__ void tconv_list(const float* wg, const float* wu, const float* wd, const float* win, const float* wout, unsigned char* ws, const int ntiles, LAS float* t, const int wv) {
;     ...
; #pragma unroll
;         for (int e = 0; e < 8; ++e) { const int idx = e * 512 + tid, r = idx >> 6, c = idx & 63; t[r * 65 + c] = cur[e]; }
;         __syncthreads();
; #pragma unroll
;         for (int e = 0; e < 4; ++e) { const int idx = e * 512 + tid, n = idx >> 5, kp = idx & 31;
;             const unsigned w = pg8::cvt_pk_bf16(t[(2 * kp) * 65 + n], t[(2 * kp + 1) * 65 + n]);
;             *(unsigned*)(d.Bt + (size_t)(d.brow0 + n) * d.K + d.k0 + 2 * kp) = w; }
;         __syncthreads();
; #pragma unroll
;         for (int e = 0; e < 8; ++e) cur[e] = nxt[e];
.Ltc4_havea:
	ds_write_b32 v5, v8 offset:0
	ds_write_b32 v5, v9 offset:2080
	ds_write_b32 v5, v10 offset:4160
	ds_write_b32 v5, v11 offset:6240
	ds_write_b32 v5, v12 offset:8320
	ds_write_b32 v5, v13 offset:10400
	ds_write_b32 v5, v14 offset:12480
	ds_write_b32 v5, v15 offset:14560
	v_mad_u32_u24 v4, v2, s30, v3
	s_waitcnt lgkmcnt(0)
	s_barrier
	ds_read2_b32 v[24:25], v6 offset0:0 offset1:65
	ds_read2_b32 v[26:27], v6 offset0:16 offset1:81
	ds_read2_b32 v[28:29], v6 offset0:32 offset1:97
	ds_read2_b32 v[30:31], v6 offset0:48 offset1:113
	s_waitcnt lgkmcnt(3)
	v_cvt_pk_bf16_f32 v32, v24, v25
	s_waitcnt lgkmcnt(2)
	v_cvt_pk_bf16_f32 v33, v26, v27
	s_waitcnt lgkmcnt(1)
	v_cvt_pk_bf16_f32 v34, v28, v29
	s_waitcnt lgkmcnt(0)
	v_cvt_pk_bf16_f32 v35, v30, v31
	global_store_dword v4, v32, s[8:9]
	s_add_u32 s8, s8, s17
	s_addc_u32 s9, s9, 0
	global_store_dword v4, v33, s[8:9]
	s_add_u32 s8, s8, s17
	s_addc_u32 s9, s9, 0
	global_store_dword v4, v34, s[8:9]
	s_add_u32 s8, s8, s17
	s_addc_u32 s9, s9, 0
	global_store_dword v4, v35, s[8:9]
	s_barrier
	s_cmp_eq_u32 s31, 0
	s_cbranch_scc1 .Ltc4_done
	s_mov_b32 s17, s15
	s_mov_b32 s30, s16
	s_mov_b64 s[8:9], s[12:13]
	s_add_u32 s4, s4, 224
	s_cmp_lt_u32 s4, 1120
	s_cselect_b32 s31, 1, 0
	s_cbranch_scc0 .Ltc4_nonextb
	v_writelane_b32 v40, s8, 32
	v_writelane_b32 v40, s9, 33
	s_cmp_lt_u32 s4, 704
	s_cbranch_scc0 .Ltc4_seg1_2
	s_mov_b32 s7, s4
	s_and_b32 s8, s7, 15
	s_lshr_b32 s9, s7, 4
	s_mul_i32 s7, s8, 720896
	s_lshl_b32 s29, s9, 8
	s_add_u32 s7, s7, s29
	s_mul_i32 s29, s28, 11264
	s_add_u32 s7, s7, s29
	s_add_u32 s10, s18, s7
	s_addc_u32 s11, s19, 0
	s_lshr_b32 s7, s9, 1
	s_lshl_b32 s7, s7, 8
	s_and_b32 s29, s9, 1
	s_lshl_b32 s29, s29, 6
	s_add_u32 s7, s7, s29
	s_mul_i32 s7, s7, 2048
	s_lshl_b32 s29, s8, 7
	s_add_u32 s7, s7, s29
	s_mul_i32 s29, s28, 4096
	s_add_u32 s7, s7, s29
	s_add_u32 s12, s26, 0x2100000
	s_addc_u32 s13, s27, 0
	s_add_u32 s12, s12, s7
	s_addc_u32 s13, s13, 0
	s_mov_b32 s14, 90112
	s_mov_b32 s15, 32768
	s_movk_i32 s16, 2048
	s_branch .Ltc4_segend_2
